# P5/P6 K-loops: reversed priority roles (loading segment prio 1, MFMA burst prio 0)
# speedup vs baseline: 1.0037x; 1.0033x over previous
; #define PG8_LDA(dst, b, h) do { if constexpr (FP8) { _Pragma("unroll") for (int m = 0; m < 4; ++m) dst##8[m] = PG8_LD8(PG8_SA(b, h), aoff, aoff1, m); } \
;         else { _Pragma("unroll") for (int m = 0; m < 4; ++m) _Pragma("unroll") for (int k = 0; k < 2; ++k) dst[m][k] = *(const LAS bf16x8*)(lds + PG8_SA(b, h) + (k ? aoff1 : aoff) + m * 2048); } } while (0)
; #define PG8_LDB(dst, b, h) do { if constexpr (FP8) { dst##8[0] = PG8_LD8(PG8_SB(b, h), boff, boff1, 0); dst##8[1] = PG8_LD8(PG8_SB(b, h), boff, boff1, 1); } \
;         else { _Pragma("unroll") for (int n = 0; n < 2; ++n) _Pragma("unroll") for (int k = 0; k < 2; ++k) dst[n][k] = *(const LAS bf16x8*)(lds + PG8_SB(b, h) + (k ? boff1 : boff) + n * 2048); } } while (0)
; #define PG8_WAIT_V(n) asm volatile("s_waitcnt vmcnt(" #n ")" ::: "memory")
; #define PG8_WAIT_L(n) asm volatile("s_waitcnt lgkmcnt(" #n ")" ::: "memory")
; #define PG8_BAR __builtin_amdgcn_s_barrier()
; #define PG8_SCHED __builtin_amdgcn_sched_barrier(0)
; #define PG8_S1 PG8_STAGE(PG8_SA(1, 1), a1 + hstepA, voffA)
; #define PG8_S2 do { PG8_STAGE(PG8_SB(0, 0), b2, voffB); PG8_STAGE(PG8_SB(0, 1), b2 + hstepB, voffB); PG8_STAGE(PG8_SA(0, 0), a2, voffA); } while (0)
; template <class Epi, class SchedT, bool ALIGN_EPI, bool SP2, bool FP8 = false>
; __device__ __forceinline__ void gemm_phase(LAS unsigned char* lds, const Gemm g, const SchedT& S, const Epi& E, const int wid) {
;     ...
;             const bool last = (t == nt - 2);
;             const char* a1 = cA + (size_t)(t + 1) * kstep;
;             const char* a2 = last ? nA : cA + (size_t)(t + 2) * kstep; const char* b2 = last ? nB : cB + (size_t)(t + 2) * kstep;
;             const char* a3 = a2 + kstep; const char* b3 = b2 + kstep;
;             if constexpr (SP2) {
;     ...
;             PG8_LDB(B0, 0, 0); PG8_LDB(B1, 0, 1); PG8_SCHED; PG8_LDA(At, 0, 0); PG8_S1;
;             PG8_WAIT_V(8); PG8_WAIT_L(0); PG8_BAR; PG8_MMAP(0, 0, 0); PG8_BAR; PG8_SCHED;
;             PG8_LDA(At, 0, 1); PG8_S2;
;             PG8_WAIT_V(8); PG8_WAIT_L(0); PG8_BAR; PG8_MMAP(1, 0, 1); PG8_BAR; PG8_SCHED;
.LBB0_899:
	ds_read_b128 v[128:131], v173
	ds_read_b128 v[132:135], v173 offset:1024
	ds_read_b128 v[136:139], v174
	ds_read_b128 v[140:143], v174 offset:1024
	ds_read_b128 v[150:153], v175
	ds_read_b128 v[154:157], v175 offset:1024
	ds_read_b128 v[158:161], v176
	ds_read_b128 v[162:165], v176 offset:1024
	s_add_i32 s35, s34, 2
	s_add_u32 s16, s48, 0xfffc0080
	s_addc_u32 s17, s49, -1
	s_cmp_eq_u32 s27, s34
	s_cselect_b32 s51, s15, s17
	s_cselect_b32 s50, s21, s16
	s_cselect_b32 s53, s24, s31
	s_cselect_b32 s52, s25, s30
	v_mov_b32_e32 v144, v168
	ds_read_b128 v[182:185], v177
	ds_read_b128 v[186:189], v177 offset:1024
	ds_read_b128 v[190:193], v177 offset:2048
	ds_read_b128 v[194:197], v177 offset:3072
	ds_read_b128 v[198:201], v177 offset:4096
	ds_read_b128 v[202:205], v177 offset:5120
	ds_read_b128 v[206:209], v177 offset:6144
	ds_read_b128 v[210:213], v177 offset:7168
	s_add_i32 m0, s87, 0xc000
	s_nop 0
	global_load_lds_dwordx4 v144, s[48:49]
	v_mov_b32_e32 v144, v170
	s_add_i32 m0, s87, 0xe000
	s_nop 0
	global_load_lds_dwordx4 v144, s[48:49]
	s_waitcnt vmcnt(8)
	s_waitcnt lgkmcnt(0)
	s_barrier
	s_setprio 0
	s_waitcnt lgkmcnt(0)
	v_mfma_f32_16x16x32_bf16 v[124:127], v[128:131], v[182:185], v[124:127]
	v_mfma_f32_16x16x32_bf16 v[120:123], v[136:139], v[182:185], v[120:123]
	v_mfma_f32_16x16x32_bf16 v[108:111], v[128:131], v[190:193], v[108:111]
	v_mfma_f32_16x16x32_bf16 v[104:107], v[136:139], v[190:193], v[104:107]
	v_mfma_f32_16x16x32_bf16 v[92:95], v[128:131], v[198:201], v[92:95]
	v_mfma_f32_16x16x32_bf16 v[88:91], v[136:139], v[198:201], v[88:91]
	v_mfma_f32_16x16x32_bf16 v[76:79], v[128:131], v[206:209], v[76:79]
	v_mfma_f32_16x16x32_bf16 v[72:75], v[136:139], v[206:209], v[72:75]
	v_mfma_f32_16x16x32_bf16 v[124:127], v[132:135], v[186:189], v[124:127]
	v_mfma_f32_16x16x32_bf16 v[120:123], v[140:143], v[186:189], v[120:123]
	v_mfma_f32_16x16x32_bf16 v[108:111], v[132:135], v[194:197], v[108:111]
	v_mfma_f32_16x16x32_bf16 v[104:107], v[140:143], v[194:197], v[104:107]
	v_mfma_f32_16x16x32_bf16 v[92:95], v[132:135], v[202:205], v[92:95]
	v_mfma_f32_16x16x32_bf16 v[88:91], v[140:143], v[202:205], v[88:91]
	v_mfma_f32_16x16x32_bf16 v[76:79], v[132:135], v[210:213], v[76:79]
	v_mfma_f32_16x16x32_bf16 v[72:75], v[140:143], v[210:213], v[72:75]
	v_mfma_f32_16x16x32_bf16 v[116:119], v[150:153], v[182:185], v[116:119]
	v_mfma_f32_16x16x32_bf16 v[112:115], v[158:161], v[182:185], v[112:115]
	v_mfma_f32_16x16x32_bf16 v[100:103], v[150:153], v[190:193], v[100:103]
	v_mfma_f32_16x16x32_bf16 v[96:99], v[158:161], v[190:193], v[96:99]
	v_mfma_f32_16x16x32_bf16 v[84:87], v[150:153], v[198:201], v[84:87]
	v_mfma_f32_16x16x32_bf16 v[80:83], v[158:161], v[198:201], v[80:83]
	v_mfma_f32_16x16x32_bf16 v[68:71], v[150:153], v[206:209], v[68:71]
	v_mfma_f32_16x16x32_bf16 v[64:67], v[158:161], v[206:209], v[64:67]
	v_mfma_f32_16x16x32_bf16 v[116:119], v[154:157], v[186:189], v[116:119]
	v_mfma_f32_16x16x32_bf16 v[112:115], v[162:165], v[186:189], v[112:115]
	v_mfma_f32_16x16x32_bf16 v[100:103], v[154:157], v[194:197], v[100:103]
	v_mfma_f32_16x16x32_bf16 v[96:99], v[162:165], v[194:197], v[96:99]
	v_mfma_f32_16x16x32_bf16 v[84:87], v[154:157], v[202:205], v[84:87]
	v_mfma_f32_16x16x32_bf16 v[80:83], v[162:165], v[202:205], v[80:83]
	v_mfma_f32_16x16x32_bf16 v[68:71], v[154:157], v[210:213], v[68:71]
	v_mfma_f32_16x16x32_bf16 v[64:67], v[162:165], v[210:213], v[64:67]
	s_setprio 1
	s_barrier
	v_mov_b32_e32 v144, v169
	s_add_i32 s16, s94, s86
	ds_read_b128 v[182:185], v177 offset:16384
	ds_read_b128 v[186:189], v177 offset:17408
	ds_read_b128 v[190:193], v177 offset:18432
	ds_read_b128 v[194:197], v177 offset:19456
	ds_read_b128 v[198:201], v177 offset:20480
	ds_read_b128 v[202:205], v177 offset:21504
	ds_read_b128 v[206:209], v177 offset:22528
	ds_read_b128 v[210:213], v177 offset:23552
	s_mov_b32 m0, s16
	s_nop 0
	global_load_lds_dwordx4 v144, s[52:53]
	v_mov_b32_e32 v144, v171
	s_add_i32 m0, s16, 0x2000
	s_add_u32 s60, s52, 0x40000
	global_load_lds_dwordx4 v144, s[52:53]
	s_addc_u32 s61, s53, 0
	v_mov_b32_e32 v144, v169
	s_add_i32 s16, s95, s86
	s_mov_b32 m0, s16
	s_nop 0
	global_load_lds_dwordx4 v144, s[60:61]
	v_mov_b32_e32 v144, v171
	s_add_i32 m0, s16, 0x2000
	s_nop 0
	global_load_lds_dwordx4 v144, s[60:61]
	v_mov_b32_e32 v144, v168
	s_mov_b32 m0, s87
	s_nop 0
	global_load_lds_dwordx4 v144, s[50:51]
	v_mov_b32_e32 v144, v170
	s_mov_b32 m0, s88
	s_nop 0
	global_load_lds_dwordx4 v144, s[50:51]
	s_waitcnt vmcnt(8)
	s_waitcnt lgkmcnt(0)
	s_barrier
; #define PG8_LDA(dst, b, h) do { if constexpr (FP8) { _Pragma("unroll") for (int m = 0; m < 4; ++m) dst##8[m] = PG8_LD8(PG8_SA(b, h), aoff, aoff1, m); } \
;         else { _Pragma("unroll") for (int m = 0; m < 4; ++m) _Pragma("unroll") for (int k = 0; k < 2; ++k) dst[m][k] = *(const LAS bf16x8*)(lds + PG8_SA(b, h) + (k ? aoff1 : aoff) + m * 2048); } } while (0)
; #define PG8_LDB(dst, b, h) do { if constexpr (FP8) { dst##8[0] = PG8_LD8(PG8_SB(b, h), boff, boff1, 0); dst##8[1] = PG8_LD8(PG8_SB(b, h), boff, boff1, 1); } \
;         else { _Pragma("unroll") for (int n = 0; n < 2; ++n) _Pragma("unroll") for (int k = 0; k < 2; ++k) dst[n][k] = *(const LAS bf16x8*)(lds + PG8_SB(b, h) + (k ? boff1 : boff) + n * 2048); } } while (0)
; #define PG8_WAIT_V(n) asm volatile("s_waitcnt vmcnt(" #n ")" ::: "memory")
; #define PG8_WAIT_L(n) asm volatile("s_waitcnt lgkmcnt(" #n ")" ::: "memory")
; #define PG8_BAR __builtin_amdgcn_s_barrier()
; #define PG8_SCHED __builtin_amdgcn_sched_barrier(0)
; #define PG8_S3 PG8_STAGE(PG8_SA(0, 1), a2 + hstepA, voffA)
; template <class Epi, class SchedT, bool ALIGN_EPI, bool SP2, bool FP8 = false>
; __device__ __forceinline__ void gemm_phase(LAS unsigned char* lds, const Gemm g, const SchedT& S, const Epi& E, const int wid) {
;     ...
;             PG8_WAIT_V(8); PG8_WAIT_L(0); PG8_BAR; PG8_MMAP(1, 0, 1); PG8_BAR; PG8_SCHED;
;             PG8_LDB(B0, 1, 0); PG8_LDB(B1, 1, 1); PG8_SCHED; PG8_LDA(At, 1, 0); PG8_S3;
;             PG8_WAIT_V(8); PG8_WAIT_L(0); PG8_BAR; PG8_MMAP(0, 1, 0); PG8_BAR; PG8_SCHED;
	s_setprio 0
	s_waitcnt lgkmcnt(0)
	v_mfma_f32_16x16x32_bf16 v[60:63], v[128:131], v[182:185], v[60:63]
	v_mfma_f32_16x16x32_bf16 v[56:59], v[136:139], v[182:185], v[56:59]
	v_mfma_f32_16x16x32_bf16 v[44:47], v[128:131], v[190:193], v[44:47]
	v_mfma_f32_16x16x32_bf16 v[40:43], v[136:139], v[190:193], v[40:43]
	v_mfma_f32_16x16x32_bf16 v[28:31], v[128:131], v[198:201], v[28:31]
	v_mfma_f32_16x16x32_bf16 v[24:27], v[136:139], v[198:201], v[24:27]
	v_mfma_f32_16x16x32_bf16 v[12:15], v[128:131], v[206:209], v[12:15]
	v_mfma_f32_16x16x32_bf16 v[8:11], v[136:139], v[206:209], v[8:11]
	v_mfma_f32_16x16x32_bf16 v[60:63], v[132:135], v[186:189], v[60:63]
	v_mfma_f32_16x16x32_bf16 v[56:59], v[140:143], v[186:189], v[56:59]
	v_mfma_f32_16x16x32_bf16 v[44:47], v[132:135], v[194:197], v[44:47]
	v_mfma_f32_16x16x32_bf16 v[40:43], v[140:143], v[194:197], v[40:43]
	v_mfma_f32_16x16x32_bf16 v[28:31], v[132:135], v[202:205], v[28:31]
	v_mfma_f32_16x16x32_bf16 v[24:27], v[140:143], v[202:205], v[24:27]
	v_mfma_f32_16x16x32_bf16 v[12:15], v[132:135], v[210:213], v[12:15]
	v_mfma_f32_16x16x32_bf16 v[8:11], v[140:143], v[210:213], v[8:11]
	v_mfma_f32_16x16x32_bf16 v[52:55], v[150:153], v[182:185], v[52:55]
	v_mfma_f32_16x16x32_bf16 v[48:51], v[158:161], v[182:185], v[48:51]
	v_mfma_f32_16x16x32_bf16 v[36:39], v[150:153], v[190:193], v[36:39]
	v_mfma_f32_16x16x32_bf16 v[32:35], v[158:161], v[190:193], v[32:35]
	v_mfma_f32_16x16x32_bf16 v[20:23], v[150:153], v[198:201], v[20:23]
	v_mfma_f32_16x16x32_bf16 v[16:19], v[158:161], v[198:201], v[16:19]
	v_mfma_f32_16x16x32_bf16 v[4:7], v[150:153], v[206:209], v[4:7]
	v_mfma_f32_16x16x32_bf16 v[0:3], v[158:161], v[206:209], v[0:3]
	v_mfma_f32_16x16x32_bf16 v[52:55], v[154:157], v[186:189], v[52:55]
	v_mfma_f32_16x16x32_bf16 v[48:51], v[162:165], v[186:189], v[48:51]
	v_mfma_f32_16x16x32_bf16 v[36:39], v[154:157], v[194:197], v[36:39]
	v_mfma_f32_16x16x32_bf16 v[32:35], v[162:165], v[194:197], v[32:35]
	v_mfma_f32_16x16x32_bf16 v[20:23], v[154:157], v[202:205], v[20:23]
	v_mfma_f32_16x16x32_bf16 v[16:19], v[162:165], v[202:205], v[16:19]
	v_mfma_f32_16x16x32_bf16 v[4:7], v[154:157], v[210:213], v[4:7]
	v_mfma_f32_16x16x32_bf16 v[0:3], v[162:165], v[210:213], v[0:3]
	s_setprio 1
	s_barrier
	s_add_i32 s16, 0, 0x18000
	s_add_i32 s17, 0, 0x1c000
	v_add_u32_e32 v132, s16, v172
	v_add_u32_e32 v144, s17, v172
	ds_read_b128 v[128:131], v132
	ds_read_b128 v[132:135], v132 offset:1024
	ds_read_b128 v[136:139], v178
	ds_read_b128 v[140:143], v178 offset:1024
	ds_read_b128 v[150:153], v144
	ds_read_b128 v[154:157], v144 offset:1024
	ds_read_b128 v[158:161], v179
	ds_read_b128 v[162:165], v179 offset:1024
	s_add_u32 s60, s50, 0x40000
	v_mov_b32_e32 v144, v168
	s_mov_b32 m0, s89
	ds_read_b128 v[182:185], v177 offset:32768
	ds_read_b128 v[186:189], v177 offset:33792
	ds_read_b128 v[190:193], v177 offset:34816
	ds_read_b128 v[194:197], v177 offset:35840
	ds_read_b128 v[198:201], v177 offset:36864
	ds_read_b128 v[202:205], v177 offset:37888
	ds_read_b128 v[206:209], v177 offset:38912
	ds_read_b128 v[210:213], v177 offset:39936
	s_addc_u32 s61, s51, 0
	s_nop 0
	global_load_lds_dwordx4 v144, s[60:61]
	v_mov_b32_e32 v144, v170
	s_mov_b32 m0, s90
	s_nop 0
	global_load_lds_dwordx4 v144, s[60:61]
	s_waitcnt vmcnt(8)
	s_waitcnt lgkmcnt(0)
	s_barrier
	s_setprio 0
	s_waitcnt lgkmcnt(0)
	v_mfma_f32_16x16x32_bf16 v[124:127], v[128:131], v[182:185], v[124:127]
	v_mfma_f32_16x16x32_bf16 v[120:123], v[136:139], v[182:185], v[120:123]
	v_mfma_f32_16x16x32_bf16 v[108:111], v[128:131], v[190:193], v[108:111]
	v_mfma_f32_16x16x32_bf16 v[104:107], v[136:139], v[190:193], v[104:107]
	v_mfma_f32_16x16x32_bf16 v[92:95], v[128:131], v[198:201], v[92:95]
	v_mfma_f32_16x16x32_bf16 v[88:91], v[136:139], v[198:201], v[88:91]
	v_mfma_f32_16x16x32_bf16 v[76:79], v[128:131], v[206:209], v[76:79]
	v_mfma_f32_16x16x32_bf16 v[72:75], v[136:139], v[206:209], v[72:75]
	v_mfma_f32_16x16x32_bf16 v[124:127], v[132:135], v[186:189], v[124:127]
	v_mfma_f32_16x16x32_bf16 v[120:123], v[140:143], v[186:189], v[120:123]
	v_mfma_f32_16x16x32_bf16 v[108:111], v[132:135], v[194:197], v[108:111]
	v_mfma_f32_16x16x32_bf16 v[104:107], v[140:143], v[194:197], v[104:107]
	v_mfma_f32_16x16x32_bf16 v[92:95], v[132:135], v[202:205], v[92:95]
	v_mfma_f32_16x16x32_bf16 v[88:91], v[140:143], v[202:205], v[88:91]
	v_mfma_f32_16x16x32_bf16 v[76:79], v[132:135], v[210:213], v[76:79]
	v_mfma_f32_16x16x32_bf16 v[72:75], v[140:143], v[210:213], v[72:75]
	v_mfma_f32_16x16x32_bf16 v[116:119], v[150:153], v[182:185], v[116:119]
	v_mfma_f32_16x16x32_bf16 v[112:115], v[158:161], v[182:185], v[112:115]
	v_mfma_f32_16x16x32_bf16 v[100:103], v[150:153], v[190:193], v[100:103]
	v_mfma_f32_16x16x32_bf16 v[96:99], v[158:161], v[190:193], v[96:99]
	v_mfma_f32_16x16x32_bf16 v[84:87], v[150:153], v[198:201], v[84:87]
	v_mfma_f32_16x16x32_bf16 v[80:83], v[158:161], v[198:201], v[80:83]
	v_mfma_f32_16x16x32_bf16 v[68:71], v[150:153], v[206:209], v[68:71]
	v_mfma_f32_16x16x32_bf16 v[64:67], v[158:161], v[206:209], v[64:67]
	v_mfma_f32_16x16x32_bf16 v[116:119], v[154:157], v[186:189], v[116:119]
	v_mfma_f32_16x16x32_bf16 v[112:115], v[162:165], v[186:189], v[112:115]
	v_mfma_f32_16x16x32_bf16 v[100:103], v[154:157], v[194:197], v[100:103]
	v_mfma_f32_16x16x32_bf16 v[96:99], v[162:165], v[194:197], v[96:99]
	v_mfma_f32_16x16x32_bf16 v[84:87], v[154:157], v[202:205], v[84:87]
	v_mfma_f32_16x16x32_bf16 v[80:83], v[162:165], v[202:205], v[80:83]
	v_mfma_f32_16x16x32_bf16 v[68:71], v[154:157], v[210:213], v[68:71]
	v_mfma_f32_16x16x32_bf16 v[64:67], v[162:165], v[210:213], v[64:67]
	s_setprio 1
	s_barrier
; #define PG8_LDA(dst, b, h) do { if constexpr (FP8) { _Pragma("unroll") for (int m = 0; m < 4; ++m) dst##8[m] = PG8_LD8(PG8_SA(b, h), aoff, aoff1, m); } \
;         else { _Pragma("unroll") for (int m = 0; m < 4; ++m) _Pragma("unroll") for (int k = 0; k < 2; ++k) dst[m][k] = *(const LAS bf16x8*)(lds + PG8_SA(b, h) + (k ? aoff1 : aoff) + m * 2048); } } while (0)
; #define PG8_WAIT_V(n) asm volatile("s_waitcnt vmcnt(" #n ")" ::: "memory")
; #define PG8_WAIT_L(n) asm volatile("s_waitcnt lgkmcnt(" #n ")" ::: "memory")
; #define PG8_BAR __builtin_amdgcn_s_barrier()
; #define PG8_SCHED __builtin_amdgcn_sched_barrier(0)
; #define PG8_S4 do { PG8_STAGE(PG8_SB(1, 0), b3, voffB); PG8_STAGE(PG8_SB(1, 1), b3 + hstepB, voffB); PG8_STAGE(PG8_SA(1, 0), a3, voffA); } while (0)
; template <class Epi, class SchedT, bool ALIGN_EPI, bool SP2, bool FP8 = false>
; __device__ __forceinline__ void gemm_phase(LAS unsigned char* lds, const Gemm g, const SchedT& S, const Epi& E, const int wid) {
;     ...
;         for (int t = 0; t < nt; t += 2) {
;     ...
;             PG8_LDA(At, 1, 1); PG8_S4;
;             PG8_WAIT_V(8); PG8_WAIT_L(0); PG8_BAR; PG8_MMAP(1, 1, 1); PG8_BAR; PG8_SCHED;
	v_mov_b32_e32 v144, v169
	ds_read_b128 v[182:185], v177 offset:49152
	ds_read_b128 v[186:189], v177 offset:50176
	ds_read_b128 v[190:193], v177 offset:51200
	ds_read_b128 v[194:197], v177 offset:52224
	ds_read_b128 v[198:201], v177 offset:53248
	ds_read_b128 v[202:205], v177 offset:54272
	ds_read_b128 v[206:209], v177 offset:55296
	ds_read_b128 v[210:213], v177 offset:56320
	s_add_i32 s16, s16, s86
	v_lshl_add_u64 v[166:167], s[52:53], 0, v[144:145]
	v_lshl_add_u64 v[166:167], v[166:167], 0, s[6:7]
	s_mov_b32 m0, s16
	v_mov_b32_e32 v144, v171
	global_load_lds_dwordx4 v[166:167], off
	s_add_i32 m0, s16, 0x2000
	s_nop 0
	v_lshl_add_u64 v[166:167], s[52:53], 0, v[144:145]
	s_add_u32 s52, s52, 0x40080
	v_lshl_add_u64 v[166:167], v[166:167], 0, s[6:7]
	s_addc_u32 s53, s53, 0
	v_mov_b32_e32 v144, v169
	s_add_i32 s16, s17, s86
	global_load_lds_dwordx4 v[166:167], off
	s_mov_b32 m0, s16
	s_nop 0
	global_load_lds_dwordx4 v144, s[52:53]
	v_mov_b32_e32 v144, v171
	s_add_i32 m0, s16, 0x2000
	s_nop 0
	global_load_lds_dwordx4 v144, s[52:53]
	v_mov_b32_e32 v144, v168
	s_mov_b32 m0, s92
	v_lshl_add_u64 v[166:167], s[50:51], 0, v[144:145]
	v_lshl_add_u64 v[166:167], v[166:167], 0, s[6:7]
	v_mov_b32_e32 v144, v170
	global_load_lds_dwordx4 v[166:167], off
	s_mov_b32 m0, s93
	v_lshl_add_u64 v[166:167], s[50:51], 0, v[144:145]
	v_lshl_add_u64 v[166:167], v[166:167], 0, s[6:7]
	global_load_lds_dwordx4 v[166:167], off
	s_waitcnt vmcnt(8)
	s_waitcnt lgkmcnt(0)
	s_barrier
	s_setprio 0
	s_waitcnt lgkmcnt(0)
	v_mfma_f32_16x16x32_bf16 v[60:63], v[128:131], v[182:185], v[60:63]
	v_mfma_f32_16x16x32_bf16 v[56:59], v[136:139], v[182:185], v[56:59]
	v_mfma_f32_16x16x32_bf16 v[44:47], v[128:131], v[190:193], v[44:47]
	v_mfma_f32_16x16x32_bf16 v[40:43], v[136:139], v[190:193], v[40:43]
	v_mfma_f32_16x16x32_bf16 v[28:31], v[128:131], v[198:201], v[28:31]
	v_mfma_f32_16x16x32_bf16 v[24:27], v[136:139], v[198:201], v[24:27]
	v_mfma_f32_16x16x32_bf16 v[12:15], v[128:131], v[206:209], v[12:15]
	v_mfma_f32_16x16x32_bf16 v[8:11], v[136:139], v[206:209], v[8:11]
	v_mfma_f32_16x16x32_bf16 v[60:63], v[132:135], v[186:189], v[60:63]
	v_mfma_f32_16x16x32_bf16 v[56:59], v[140:143], v[186:189], v[56:59]
	v_mfma_f32_16x16x32_bf16 v[44:47], v[132:135], v[194:197], v[44:47]
	v_mfma_f32_16x16x32_bf16 v[40:43], v[140:143], v[194:197], v[40:43]
	v_mfma_f32_16x16x32_bf16 v[28:31], v[132:135], v[202:205], v[28:31]
	v_mfma_f32_16x16x32_bf16 v[24:27], v[140:143], v[202:205], v[24:27]
	v_mfma_f32_16x16x32_bf16 v[12:15], v[132:135], v[210:213], v[12:15]
	v_mfma_f32_16x16x32_bf16 v[8:11], v[140:143], v[210:213], v[8:11]
	v_mfma_f32_16x16x32_bf16 v[52:55], v[150:153], v[182:185], v[52:55]
	v_mfma_f32_16x16x32_bf16 v[48:51], v[158:161], v[182:185], v[48:51]
	v_mfma_f32_16x16x32_bf16 v[36:39], v[150:153], v[190:193], v[36:39]
	v_mfma_f32_16x16x32_bf16 v[32:35], v[158:161], v[190:193], v[32:35]
	v_mfma_f32_16x16x32_bf16 v[20:23], v[150:153], v[198:201], v[20:23]
	v_mfma_f32_16x16x32_bf16 v[16:19], v[158:161], v[198:201], v[16:19]
	v_mfma_f32_16x16x32_bf16 v[4:7], v[150:153], v[206:209], v[4:7]
	v_mfma_f32_16x16x32_bf16 v[0:3], v[158:161], v[206:209], v[0:3]
	v_mfma_f32_16x16x32_bf16 v[52:55], v[154:157], v[186:189], v[52:55]
	v_mfma_f32_16x16x32_bf16 v[48:51], v[162:165], v[186:189], v[48:51]
	v_mfma_f32_16x16x32_bf16 v[36:39], v[154:157], v[194:197], v[36:39]
	v_mfma_f32_16x16x32_bf16 v[32:35], v[162:165], v[194:197], v[32:35]
	v_mfma_f32_16x16x32_bf16 v[20:23], v[154:157], v[202:205], v[20:23]
	v_mfma_f32_16x16x32_bf16 v[16:19], v[162:165], v[202:205], v[16:19]
	v_mfma_f32_16x16x32_bf16 v[4:7], v[154:157], v[210:213], v[4:7]
	v_mfma_f32_16x16x32_bf16 v[0:3], v[162:165], v[210:213], v[0:3]
	s_setprio 1
	s_barrier
	s_add_u32 s48, s48, 0x100
	s_addc_u32 s49, s49, 0
	s_add_u32 s30, s30, 0x100
	s_addc_u32 s31, s31, 0
	s_cmp_ge_i32 s35, s20
	s_mov_b32 s34, s35
	s_cbranch_scc0 .LBB0_899
	s_setprio 0
	s_branch .LBB0_894

; #define PG8_LDA(dst, b, h) do { if constexpr (FP8) { _Pragma("unroll") for (int m = 0; m < 4; ++m) dst##8[m] = PG8_LD8(PG8_SA(b, h), aoff, aoff1, m); } \
;         else { _Pragma("unroll") for (int m = 0; m < 4; ++m) _Pragma("unroll") for (int k = 0; k < 2; ++k) dst[m][k] = *(const LAS bf16x8*)(lds + PG8_SA(b, h) + (k ? aoff1 : aoff) + m * 2048); } } while (0)
; #define PG8_LDB(dst, b, h) do { if constexpr (FP8) { dst##8[0] = PG8_LD8(PG8_SB(b, h), boff, boff1, 0); dst##8[1] = PG8_LD8(PG8_SB(b, h), boff, boff1, 1); } \
;         else { _Pragma("unroll") for (int n = 0; n < 2; ++n) _Pragma("unroll") for (int k = 0; k < 2; ++k) dst[n][k] = *(const LAS bf16x8*)(lds + PG8_SB(b, h) + (k ? boff1 : boff) + n * 2048); } } while (0)
; #define PG8_WAIT_V(n) asm volatile("s_waitcnt vmcnt(" #n ")" ::: "memory")
; #define PG8_WAIT_L(n) asm volatile("s_waitcnt lgkmcnt(" #n ")" ::: "memory")
; #define PG8_BAR __builtin_amdgcn_s_barrier()
; #define PG8_SCHED __builtin_amdgcn_sched_barrier(0)
; #define PG8_S1 PG8_STAGE(PG8_SA(1, 1), a1 + hstepA, voffA)
; #define PG8_S2 do { PG8_STAGE(PG8_SB(0, 0), b2, voffB); PG8_STAGE(PG8_SB(0, 1), b2 + hstepB, voffB); PG8_STAGE(PG8_SA(0, 0), a2, voffA); } while (0)
; template <class Epi, class SchedT, bool ALIGN_EPI, bool SP2, bool FP8 = false>
; __device__ __forceinline__ void gemm_phase(LAS unsigned char* lds, const Gemm g, const SchedT& S, const Epi& E, const int wid) {
;     ...
;             const bool last = (t == nt - 2);
;             const char* a1 = cA + (size_t)(t + 1) * kstep;
;             const char* a2 = last ? nA : cA + (size_t)(t + 2) * kstep; const char* b2 = last ? nB : cB + (size_t)(t + 2) * kstep;
;             const char* a3 = a2 + kstep; const char* b3 = b2 + kstep;
;             if constexpr (SP2) {
;     ...
;             PG8_LDB(B0, 0, 0); PG8_LDB(B1, 0, 1); PG8_SCHED; PG8_LDA(At, 0, 0); PG8_S1;
;             PG8_WAIT_V(8); PG8_WAIT_L(0); PG8_BAR; PG8_MMAP(0, 0, 0); PG8_BAR; PG8_SCHED;
;             PG8_LDA(At, 0, 1); PG8_S2;
;             PG8_WAIT_V(8); PG8_WAIT_L(0); PG8_BAR; PG8_MMAP(1, 0, 1); PG8_BAR; PG8_SCHED;
.LBB0_970:
	ds_read_b128 v[134:137], v175
	ds_read_b128 v[138:141], v175 offset:1024
	ds_read_b128 v[142:145], v176
	ds_read_b128 v[146:149], v176 offset:1024
	ds_read_b128 v[150:153], v177
	ds_read_b128 v[154:157], v177 offset:1024
	ds_read_b128 v[158:161], v178
	ds_read_b128 v[162:165], v178 offset:1024
	s_add_i32 s48, s34, 2
	s_add_u32 s16, s24, 0xfff00080
	s_addc_u32 s17, s25, -1
	s_cmp_eq_u32 s45, s34
	s_cselect_b32 s34, s15, s16
	s_cselect_b32 s35, s13, s17
	s_cselect_b32 s39, s27, s47
	s_cselect_b32 s38, s31, s46
	v_mov_b32_e32 v128, v172
	ds_read_b128 v[166:169], v179
	ds_read_b128 v[184:187], v179 offset:1024
	ds_read_b128 v[188:191], v179 offset:2048
	ds_read_b128 v[192:195], v179 offset:3072
	ds_read_b128 v[196:199], v179 offset:4096
	ds_read_b128 v[200:203], v179 offset:5120
	ds_read_b128 v[204:207], v179 offset:6144
	ds_read_b128 v[208:211], v179 offset:7168
	s_add_i32 m0, s87, 0xc000
	s_nop 0
	global_load_lds_dwordx4 v128, s[24:25]
	v_mov_b32_e32 v128, v173
	s_add_i32 m0, s87, 0xe000
	s_nop 0
	global_load_lds_dwordx4 v128, s[24:25]
	s_waitcnt vmcnt(8)
	s_waitcnt lgkmcnt(0)
	s_barrier
	s_setprio 0
	s_waitcnt lgkmcnt(0)
	v_mfma_f32_16x16x32_bf16 v[124:127], v[134:137], v[166:169], v[124:127]
	v_mfma_f32_16x16x32_bf16 v[120:123], v[142:145], v[166:169], v[120:123]
	v_mfma_f32_16x16x32_bf16 v[108:111], v[134:137], v[188:191], v[108:111]
	v_mfma_f32_16x16x32_bf16 v[104:107], v[142:145], v[188:191], v[104:107]
	v_mfma_f32_16x16x32_bf16 v[92:95], v[134:137], v[196:199], v[92:95]
	v_mfma_f32_16x16x32_bf16 v[88:91], v[142:145], v[196:199], v[88:91]
	v_mfma_f32_16x16x32_bf16 v[76:79], v[134:137], v[204:207], v[76:79]
	v_mfma_f32_16x16x32_bf16 v[72:75], v[142:145], v[204:207], v[72:75]
	v_mfma_f32_16x16x32_bf16 v[124:127], v[138:141], v[184:187], v[124:127]
	v_mfma_f32_16x16x32_bf16 v[120:123], v[146:149], v[184:187], v[120:123]
	v_mfma_f32_16x16x32_bf16 v[108:111], v[138:141], v[192:195], v[108:111]
	v_mfma_f32_16x16x32_bf16 v[104:107], v[146:149], v[192:195], v[104:107]
	v_mfma_f32_16x16x32_bf16 v[92:95], v[138:141], v[200:203], v[92:95]
	v_mfma_f32_16x16x32_bf16 v[88:91], v[146:149], v[200:203], v[88:91]
	v_mfma_f32_16x16x32_bf16 v[76:79], v[138:141], v[208:211], v[76:79]
	v_mfma_f32_16x16x32_bf16 v[72:75], v[146:149], v[208:211], v[72:75]
	v_mfma_f32_16x16x32_bf16 v[116:119], v[150:153], v[166:169], v[116:119]
	v_mfma_f32_16x16x32_bf16 v[112:115], v[158:161], v[166:169], v[112:115]
	v_mfma_f32_16x16x32_bf16 v[100:103], v[150:153], v[188:191], v[100:103]
	v_mfma_f32_16x16x32_bf16 v[96:99], v[158:161], v[188:191], v[96:99]
	v_mfma_f32_16x16x32_bf16 v[84:87], v[150:153], v[196:199], v[84:87]
	v_mfma_f32_16x16x32_bf16 v[80:83], v[158:161], v[196:199], v[80:83]
	v_mfma_f32_16x16x32_bf16 v[68:71], v[150:153], v[204:207], v[68:71]
	v_mfma_f32_16x16x32_bf16 v[64:67], v[158:161], v[204:207], v[64:67]
	v_mfma_f32_16x16x32_bf16 v[116:119], v[154:157], v[184:187], v[116:119]
	v_mfma_f32_16x16x32_bf16 v[112:115], v[162:165], v[184:187], v[112:115]
	v_mfma_f32_16x16x32_bf16 v[100:103], v[154:157], v[192:195], v[100:103]
	v_mfma_f32_16x16x32_bf16 v[96:99], v[162:165], v[192:195], v[96:99]
	v_mfma_f32_16x16x32_bf16 v[84:87], v[154:157], v[200:203], v[84:87]
	v_mfma_f32_16x16x32_bf16 v[80:83], v[162:165], v[200:203], v[80:83]
	v_mfma_f32_16x16x32_bf16 v[68:71], v[154:157], v[208:211], v[68:71]
	v_mfma_f32_16x16x32_bf16 v[64:67], v[162:165], v[208:211], v[64:67]
	s_setprio 1
	s_barrier
	v_mov_b32_e32 v128, v172
	s_add_i32 s16, s94, s86
	ds_read_b128 v[166:169], v179 offset:16384
	ds_read_b128 v[184:187], v179 offset:17408
	ds_read_b128 v[188:191], v179 offset:18432
	ds_read_b128 v[192:195], v179 offset:19456
	ds_read_b128 v[196:199], v179 offset:20480
	ds_read_b128 v[200:203], v179 offset:21504
	ds_read_b128 v[204:207], v179 offset:22528
	ds_read_b128 v[208:211], v179 offset:23552
	s_mov_b32 m0, s16
	s_nop 0
	global_load_lds_dwordx4 v128, s[38:39]
	v_mov_b32_e32 v128, v173
	s_add_i32 m0, s16, 0x2000
	s_add_u32 s50, s38, 0x100000
	global_load_lds_dwordx4 v128, s[38:39]
	s_addc_u32 s51, s39, 0
	v_mov_b32_e32 v128, v172
	s_add_i32 s16, s95, s86
	s_mov_b32 m0, s16
	s_nop 0
	global_load_lds_dwordx4 v128, s[50:51]
	v_mov_b32_e32 v128, v173
	s_add_i32 m0, s16, 0x2000
	s_nop 0
	global_load_lds_dwordx4 v128, s[50:51]
	v_mov_b32_e32 v128, v172
	s_mov_b32 m0, s87
	s_nop 0
	global_load_lds_dwordx4 v128, s[34:35]
	v_mov_b32_e32 v128, v173
	s_mov_b32 m0, s88
	s_nop 0
	global_load_lds_dwordx4 v128, s[34:35]
	s_waitcnt vmcnt(8)
	s_waitcnt lgkmcnt(0)
	s_barrier
; #define PG8_LDA(dst, b, h) do { if constexpr (FP8) { _Pragma("unroll") for (int m = 0; m < 4; ++m) dst##8[m] = PG8_LD8(PG8_SA(b, h), aoff, aoff1, m); } \
;         else { _Pragma("unroll") for (int m = 0; m < 4; ++m) _Pragma("unroll") for (int k = 0; k < 2; ++k) dst[m][k] = *(const LAS bf16x8*)(lds + PG8_SA(b, h) + (k ? aoff1 : aoff) + m * 2048); } } while (0)
; #define PG8_LDB(dst, b, h) do { if constexpr (FP8) { dst##8[0] = PG8_LD8(PG8_SB(b, h), boff, boff1, 0); dst##8[1] = PG8_LD8(PG8_SB(b, h), boff, boff1, 1); } \
;         else { _Pragma("unroll") for (int n = 0; n < 2; ++n) _Pragma("unroll") for (int k = 0; k < 2; ++k) dst[n][k] = *(const LAS bf16x8*)(lds + PG8_SB(b, h) + (k ? boff1 : boff) + n * 2048); } } while (0)
; #define PG8_WAIT_V(n) asm volatile("s_waitcnt vmcnt(" #n ")" ::: "memory")
; #define PG8_WAIT_L(n) asm volatile("s_waitcnt lgkmcnt(" #n ")" ::: "memory")
; #define PG8_BAR __builtin_amdgcn_s_barrier()
; #define PG8_SCHED __builtin_amdgcn_sched_barrier(0)
; #define PG8_S3 PG8_STAGE(PG8_SA(0, 1), a2 + hstepA, voffA)
; template <class Epi, class SchedT, bool ALIGN_EPI, bool SP2, bool FP8 = false>
; __device__ __forceinline__ void gemm_phase(LAS unsigned char* lds, const Gemm g, const SchedT& S, const Epi& E, const int wid) {
;     ...
;             PG8_WAIT_V(8); PG8_WAIT_L(0); PG8_BAR; PG8_MMAP(1, 0, 1); PG8_BAR; PG8_SCHED;
;             PG8_LDB(B0, 1, 0); PG8_LDB(B1, 1, 1); PG8_SCHED; PG8_LDA(At, 1, 0); PG8_S3;
;             PG8_WAIT_V(8); PG8_WAIT_L(0); PG8_BAR; PG8_MMAP(0, 1, 0); PG8_BAR; PG8_SCHED;
	s_setprio 0
	s_waitcnt lgkmcnt(0)
	v_mfma_f32_16x16x32_bf16 v[60:63], v[134:137], v[166:169], v[60:63]
	v_mfma_f32_16x16x32_bf16 v[56:59], v[142:145], v[166:169], v[56:59]
	v_mfma_f32_16x16x32_bf16 v[44:47], v[134:137], v[188:191], v[44:47]
	v_mfma_f32_16x16x32_bf16 v[40:43], v[142:145], v[188:191], v[40:43]
	v_mfma_f32_16x16x32_bf16 v[28:31], v[134:137], v[196:199], v[28:31]
	v_mfma_f32_16x16x32_bf16 v[24:27], v[142:145], v[196:199], v[24:27]
	v_mfma_f32_16x16x32_bf16 v[12:15], v[134:137], v[204:207], v[12:15]
	v_mfma_f32_16x16x32_bf16 v[8:11], v[142:145], v[204:207], v[8:11]
	v_mfma_f32_16x16x32_bf16 v[60:63], v[138:141], v[184:187], v[60:63]
	v_mfma_f32_16x16x32_bf16 v[56:59], v[146:149], v[184:187], v[56:59]
	v_mfma_f32_16x16x32_bf16 v[44:47], v[138:141], v[192:195], v[44:47]
	v_mfma_f32_16x16x32_bf16 v[40:43], v[146:149], v[192:195], v[40:43]
	v_mfma_f32_16x16x32_bf16 v[28:31], v[138:141], v[200:203], v[28:31]
	v_mfma_f32_16x16x32_bf16 v[24:27], v[146:149], v[200:203], v[24:27]
	v_mfma_f32_16x16x32_bf16 v[12:15], v[138:141], v[208:211], v[12:15]
	v_mfma_f32_16x16x32_bf16 v[8:11], v[146:149], v[208:211], v[8:11]
	v_mfma_f32_16x16x32_bf16 v[52:55], v[150:153], v[166:169], v[52:55]
	v_mfma_f32_16x16x32_bf16 v[48:51], v[158:161], v[166:169], v[48:51]
	v_mfma_f32_16x16x32_bf16 v[36:39], v[150:153], v[188:191], v[36:39]
	v_mfma_f32_16x16x32_bf16 v[32:35], v[158:161], v[188:191], v[32:35]
	v_mfma_f32_16x16x32_bf16 v[20:23], v[150:153], v[196:199], v[20:23]
	v_mfma_f32_16x16x32_bf16 v[16:19], v[158:161], v[196:199], v[16:19]
	v_mfma_f32_16x16x32_bf16 v[4:7], v[150:153], v[204:207], v[4:7]
	v_mfma_f32_16x16x32_bf16 v[0:3], v[158:161], v[204:207], v[0:3]
	v_mfma_f32_16x16x32_bf16 v[52:55], v[154:157], v[184:187], v[52:55]
	v_mfma_f32_16x16x32_bf16 v[48:51], v[162:165], v[184:187], v[48:51]
	v_mfma_f32_16x16x32_bf16 v[36:39], v[154:157], v[192:195], v[36:39]
	v_mfma_f32_16x16x32_bf16 v[32:35], v[162:165], v[192:195], v[32:35]
	v_mfma_f32_16x16x32_bf16 v[20:23], v[154:157], v[200:203], v[20:23]
	v_mfma_f32_16x16x32_bf16 v[16:19], v[162:165], v[200:203], v[16:19]
	v_mfma_f32_16x16x32_bf16 v[4:7], v[154:157], v[208:211], v[4:7]
	v_mfma_f32_16x16x32_bf16 v[0:3], v[162:165], v[208:211], v[0:3]
	s_setprio 1
	s_barrier
	s_add_i32 s16, 0, 0x18000
	v_add_u32_e32 v128, s16, v174
	s_add_i32 s17, 0, 0x1c000
	ds_read_b128 v[134:137], v128
	ds_read_b128 v[138:141], v128 offset:1024
	ds_read_b128 v[142:145], v180
	ds_read_b128 v[146:149], v180 offset:1024
	v_add_u32_e32 v128, s17, v174
	ds_read_b128 v[150:153], v128
	ds_read_b128 v[154:157], v128 offset:1024
	ds_read_b128 v[158:161], v181
	ds_read_b128 v[162:165], v181 offset:1024
	s_add_u32 s50, s34, 0x100000
	v_mov_b32_e32 v128, v172
	s_mov_b32 m0, s89
	ds_read_b128 v[166:169], v179 offset:32768
	ds_read_b128 v[184:187], v179 offset:33792
	ds_read_b128 v[188:191], v179 offset:34816
	ds_read_b128 v[192:195], v179 offset:35840
	ds_read_b128 v[196:199], v179 offset:36864
	ds_read_b128 v[200:203], v179 offset:37888
	ds_read_b128 v[204:207], v179 offset:38912
	ds_read_b128 v[208:211], v179 offset:39936
	s_addc_u32 s51, s35, 0
	s_nop 0
	global_load_lds_dwordx4 v128, s[50:51]
	v_mov_b32_e32 v128, v173
	s_mov_b32 m0, s90
	s_nop 0
	global_load_lds_dwordx4 v128, s[50:51]
	s_waitcnt vmcnt(8)
	s_waitcnt lgkmcnt(0)
	s_barrier
	s_setprio 0
	s_waitcnt lgkmcnt(0)
	v_mfma_f32_16x16x32_bf16 v[124:127], v[134:137], v[166:169], v[124:127]
	v_mfma_f32_16x16x32_bf16 v[120:123], v[142:145], v[166:169], v[120:123]
	v_mfma_f32_16x16x32_bf16 v[108:111], v[134:137], v[188:191], v[108:111]
	v_mfma_f32_16x16x32_bf16 v[104:107], v[142:145], v[188:191], v[104:107]
	v_mfma_f32_16x16x32_bf16 v[92:95], v[134:137], v[196:199], v[92:95]
	v_mfma_f32_16x16x32_bf16 v[88:91], v[142:145], v[196:199], v[88:91]
	v_mfma_f32_16x16x32_bf16 v[76:79], v[134:137], v[204:207], v[76:79]
	v_mfma_f32_16x16x32_bf16 v[72:75], v[142:145], v[204:207], v[72:75]
	v_mfma_f32_16x16x32_bf16 v[124:127], v[138:141], v[184:187], v[124:127]
	v_mfma_f32_16x16x32_bf16 v[120:123], v[146:149], v[184:187], v[120:123]
	v_mfma_f32_16x16x32_bf16 v[108:111], v[138:141], v[192:195], v[108:111]
	v_mfma_f32_16x16x32_bf16 v[104:107], v[146:149], v[192:195], v[104:107]
	v_mfma_f32_16x16x32_bf16 v[92:95], v[138:141], v[200:203], v[92:95]
	v_mfma_f32_16x16x32_bf16 v[88:91], v[146:149], v[200:203], v[88:91]
	v_mfma_f32_16x16x32_bf16 v[76:79], v[138:141], v[208:211], v[76:79]
	v_mfma_f32_16x16x32_bf16 v[72:75], v[146:149], v[208:211], v[72:75]
	v_mfma_f32_16x16x32_bf16 v[116:119], v[150:153], v[166:169], v[116:119]
	v_mfma_f32_16x16x32_bf16 v[112:115], v[158:161], v[166:169], v[112:115]
	v_mfma_f32_16x16x32_bf16 v[100:103], v[150:153], v[188:191], v[100:103]
	v_mfma_f32_16x16x32_bf16 v[96:99], v[158:161], v[188:191], v[96:99]
	v_mfma_f32_16x16x32_bf16 v[84:87], v[150:153], v[196:199], v[84:87]
	v_mfma_f32_16x16x32_bf16 v[80:83], v[158:161], v[196:199], v[80:83]
	v_mfma_f32_16x16x32_bf16 v[68:71], v[150:153], v[204:207], v[68:71]
	v_mfma_f32_16x16x32_bf16 v[64:67], v[158:161], v[204:207], v[64:67]
	v_mfma_f32_16x16x32_bf16 v[116:119], v[154:157], v[184:187], v[116:119]
	v_mfma_f32_16x16x32_bf16 v[112:115], v[162:165], v[184:187], v[112:115]
	v_mfma_f32_16x16x32_bf16 v[100:103], v[154:157], v[192:195], v[100:103]
	v_mfma_f32_16x16x32_bf16 v[96:99], v[162:165], v[192:195], v[96:99]
	v_mfma_f32_16x16x32_bf16 v[84:87], v[154:157], v[200:203], v[84:87]
	v_mfma_f32_16x16x32_bf16 v[80:83], v[162:165], v[200:203], v[80:83]
	v_mfma_f32_16x16x32_bf16 v[68:71], v[154:157], v[208:211], v[68:71]
	v_mfma_f32_16x16x32_bf16 v[64:67], v[162:165], v[208:211], v[64:67]
	s_setprio 1
	s_barrier
; #define PG8_LDA(dst, b, h) do { if constexpr (FP8) { _Pragma("unroll") for (int m = 0; m < 4; ++m) dst##8[m] = PG8_LD8(PG8_SA(b, h), aoff, aoff1, m); } \
;         else { _Pragma("unroll") for (int m = 0; m < 4; ++m) _Pragma("unroll") for (int k = 0; k < 2; ++k) dst[m][k] = *(const LAS bf16x8*)(lds + PG8_SA(b, h) + (k ? aoff1 : aoff) + m * 2048); } } while (0)
; #define PG8_WAIT_V(n) asm volatile("s_waitcnt vmcnt(" #n ")" ::: "memory")
; #define PG8_WAIT_L(n) asm volatile("s_waitcnt lgkmcnt(" #n ")" ::: "memory")
; #define PG8_BAR __builtin_amdgcn_s_barrier()
; #define PG8_SCHED __builtin_amdgcn_sched_barrier(0)
; #define PG8_S4 do { PG8_STAGE(PG8_SB(1, 0), b3, voffB); PG8_STAGE(PG8_SB(1, 1), b3 + hstepB, voffB); PG8_STAGE(PG8_SA(1, 0), a3, voffA); } while (0)
; template <class Epi, class SchedT, bool ALIGN_EPI, bool SP2, bool FP8 = false>
; __device__ __forceinline__ void gemm_phase(LAS unsigned char* lds, const Gemm g, const SchedT& S, const Epi& E, const int wid) {
;     ...
;         for (int t = 0; t < nt; t += 2) {
;     ...
;             PG8_LDA(At, 1, 1); PG8_S4;
;             PG8_WAIT_V(8); PG8_WAIT_L(0); PG8_BAR; PG8_MMAP(1, 1, 1); PG8_BAR; PG8_SCHED;
	v_mov_b32_e32 v128, v172
	ds_read_b128 v[166:169], v179 offset:49152
	ds_read_b128 v[184:187], v179 offset:50176
	ds_read_b128 v[188:191], v179 offset:51200
	ds_read_b128 v[192:195], v179 offset:52224
	ds_read_b128 v[196:199], v179 offset:53248
	ds_read_b128 v[200:203], v179 offset:54272
	ds_read_b128 v[204:207], v179 offset:55296
	ds_read_b128 v[208:211], v179 offset:56320
	s_add_i32 s16, s16, s86
	v_lshl_add_u64 v[170:171], s[38:39], 0, v[128:129]
	v_lshl_add_u64 v[170:171], v[170:171], 0, s[8:9]
	s_mov_b32 m0, s16
	v_mov_b32_e32 v128, v173
	global_load_lds_dwordx4 v[170:171], off
	s_add_i32 m0, s16, 0x2000
	s_nop 0
	v_lshl_add_u64 v[170:171], s[38:39], 0, v[128:129]
	s_add_u32 s38, s38, 0x100080
	v_lshl_add_u64 v[170:171], v[170:171], 0, s[8:9]
	s_addc_u32 s39, s39, 0
	v_mov_b32_e32 v128, v172
	s_add_i32 s16, s17, s86
	global_load_lds_dwordx4 v[170:171], off
	s_mov_b32 m0, s16
	s_nop 0
	global_load_lds_dwordx4 v128, s[38:39]
	v_mov_b32_e32 v128, v173
	s_add_i32 m0, s16, 0x2000
	s_nop 0
	global_load_lds_dwordx4 v128, s[38:39]
	v_mov_b32_e32 v128, v172
	s_mov_b32 m0, s92
	v_lshl_add_u64 v[170:171], s[34:35], 0, v[128:129]
	v_lshl_add_u64 v[170:171], v[170:171], 0, s[8:9]
	v_mov_b32_e32 v128, v173
	global_load_lds_dwordx4 v[170:171], off
	s_mov_b32 m0, s93
	v_lshl_add_u64 v[170:171], s[34:35], 0, v[128:129]
	v_lshl_add_u64 v[170:171], v[170:171], 0, s[8:9]
	global_load_lds_dwordx4 v[170:171], off
	s_waitcnt vmcnt(8)
	s_waitcnt lgkmcnt(0)
	s_barrier
	s_setprio 0
	s_waitcnt lgkmcnt(0)
	v_mfma_f32_16x16x32_bf16 v[60:63], v[134:137], v[166:169], v[60:63]
	v_mfma_f32_16x16x32_bf16 v[56:59], v[142:145], v[166:169], v[56:59]
	v_mfma_f32_16x16x32_bf16 v[44:47], v[134:137], v[188:191], v[44:47]
	v_mfma_f32_16x16x32_bf16 v[40:43], v[142:145], v[188:191], v[40:43]
	v_mfma_f32_16x16x32_bf16 v[28:31], v[134:137], v[196:199], v[28:31]
	v_mfma_f32_16x16x32_bf16 v[24:27], v[142:145], v[196:199], v[24:27]
	v_mfma_f32_16x16x32_bf16 v[12:15], v[134:137], v[204:207], v[12:15]
	v_mfma_f32_16x16x32_bf16 v[8:11], v[142:145], v[204:207], v[8:11]
	v_mfma_f32_16x16x32_bf16 v[60:63], v[138:141], v[184:187], v[60:63]
	v_mfma_f32_16x16x32_bf16 v[56:59], v[146:149], v[184:187], v[56:59]
	v_mfma_f32_16x16x32_bf16 v[44:47], v[138:141], v[192:195], v[44:47]
	v_mfma_f32_16x16x32_bf16 v[40:43], v[146:149], v[192:195], v[40:43]
	v_mfma_f32_16x16x32_bf16 v[28:31], v[138:141], v[200:203], v[28:31]
	v_mfma_f32_16x16x32_bf16 v[24:27], v[146:149], v[200:203], v[24:27]
	v_mfma_f32_16x16x32_bf16 v[12:15], v[138:141], v[208:211], v[12:15]
	v_mfma_f32_16x16x32_bf16 v[8:11], v[146:149], v[208:211], v[8:11]
	v_mfma_f32_16x16x32_bf16 v[52:55], v[150:153], v[166:169], v[52:55]
	v_mfma_f32_16x16x32_bf16 v[48:51], v[158:161], v[166:169], v[48:51]
	v_mfma_f32_16x16x32_bf16 v[36:39], v[150:153], v[188:191], v[36:39]
	v_mfma_f32_16x16x32_bf16 v[32:35], v[158:161], v[188:191], v[32:35]
	v_mfma_f32_16x16x32_bf16 v[20:23], v[150:153], v[196:199], v[20:23]
	v_mfma_f32_16x16x32_bf16 v[16:19], v[158:161], v[196:199], v[16:19]
	v_mfma_f32_16x16x32_bf16 v[4:7], v[150:153], v[204:207], v[4:7]
	v_mfma_f32_16x16x32_bf16 v[0:3], v[158:161], v[204:207], v[0:3]
	v_mfma_f32_16x16x32_bf16 v[52:55], v[154:157], v[184:187], v[52:55]
	v_mfma_f32_16x16x32_bf16 v[48:51], v[162:165], v[184:187], v[48:51]
	v_mfma_f32_16x16x32_bf16 v[36:39], v[154:157], v[192:195], v[36:39]
	v_mfma_f32_16x16x32_bf16 v[32:35], v[162:165], v[192:195], v[32:35]
	v_mfma_f32_16x16x32_bf16 v[20:23], v[154:157], v[200:203], v[20:23]
	v_mfma_f32_16x16x32_bf16 v[16:19], v[162:165], v[200:203], v[16:19]
	v_mfma_f32_16x16x32_bf16 v[4:7], v[154:157], v[208:211], v[4:7]
	v_mfma_f32_16x16x32_bf16 v[0:3], v[162:165], v[208:211], v[0:3]
	s_setprio 1
	s_barrier
	s_add_u32 s24, s24, 0x100
	s_addc_u32 s25, s25, 0
	s_add_u32 s46, s46, 0x100
	s_addc_u32 s47, s47, 0
	s_cmp_ge_i32 s48, s30
	s_mov_b32 s34, s48
	s_cbranch_scc0 .LBB0_970
	s_setprio 0
	s_and_b64 vcc, exec, s[96:97]
	s_cbranch_vccz .LBB0_973
